# NA attention: local stage accumulates o in place (32 v_mov_b64 per stage dropped), row-1 QK MFMAs issued early, DMA M0 via SALU add
# speedup vs baseline: 1.0164x; 1.0076x over previous
.LBB0_201:
	s_xor_b32 s0, s6, 0x4000
	v_add_u32_e32 v0, s9, v122
	v_add_u32_e32 v52, s0, v94
	v_lshl_or_b32 v0, v0, 10, v126
	v_readfirstlane_b32 s0, v52
	v_lshl_add_u64 v[50:51], v[0:1], 1, s[28:29]
	s_mov_b32 m0, s0
	v_add_u32_e32 v0, s9, v125
	global_load_lds_dwordx4 v[50:51], off
	v_lshl_add_u64 v[50:51], v[0:1], 1, s[58:59]
	v_add_u32_e32 v0, s9, v123
	s_add_u32 m0, s0, 0x2000
	v_lshl_or_b32 v0, v0, 10, v127
	global_load_lds_dwordx4 v[50:51], off
	v_lshl_add_u64 v[50:51], v[0:1], 1, s[28:29]
	s_add_u32 m0, s0, 0x400
	v_add_u32_e32 v0, s9, v124
	global_load_lds_dwordx4 v[50:51], off
	v_lshl_add_u64 v[50:51], v[0:1], 1, s[58:59]
	s_add_u32 m0, s0, 0x2400
	s_nop 0
	global_load_lds_dwordx4 v[50:51], off
.LBB0_202:
	v_add_u32_e32 v0, v93, v88
	v_add_u32_e32 v72, v93, v87
	ds_read_b128 v[50:53], v0 offset:32768
	ds_read_b128 v[54:57], v72 offset:32768
	ds_read_b128 v[156:159], v0 offset:40960
	ds_read_b128 v[160:163], v72 offset:40960
	v_add_u32_e32 v67, s98, v117
	v_add_u32_e32 v62, s99, v117
	s_waitcnt lgkmcnt(2)
	v_mfma_f32_16x16x32_bf16 v[58:61], v[46:49], v[50:53], 0
	v_add_u32_e32 v63, s30, v117
	v_add_u32_e32 v68, s4, v117
	s_add_i32 s10, s81, s8
	v_add_u32_e32 v66, s97, v117
	ds_read2_b32 v[64:65], v68 offset1:1
	ds_read2_b32 v[70:71], v68 offset0:2 offset1:3
	ds_read_b32 v68, v63
	ds_read_b32 v69, v62
	v_mfma_f32_16x16x32_bf16 v[60:63], v[42:45], v[54:57], v[58:61]
	s_nop 2
	ds_read_b32 v58, v67
	ds_read_b32 v59, v66
	v_add_u32_e32 v172, v128, v116
	v_add_u32_e32 v173, 0x10364, v172
	v_add_u32_e32 v174, 0x1036c, v172
	v_add_u32_e32 v175, 0x103a4, v172
	v_add_u32_e32 v172, 0x103ac, v172
	ds_read2_b32 v[164:165], v173 offset1:1
	ds_read2_b32 v[166:167], v174 offset1:1
	ds_read2_b32 v[168:169], v175 offset1:1
	ds_read2_b32 v[170:171], v172 offset1:1
	s_cmp_ge_u32 s10, s80
	s_cselect_b64 s[0:1], -1, 0
	v_mfma_f32_16x16x32_bf16 v[50:53], v[6:9], v[50:53], 0
	s_cmp_lt_u32 s10, s89
	s_cselect_b64 s[8:9], -1, 0
	s_and_b64 s[0:1], s[0:1], s[8:9]
	s_waitcnt lgkmcnt(4)
	v_mfma_f32_16x16x32_bf16 v[50:53], v[2:5], v[54:57], v[50:53]
	v_add_u32_e32 v172, s6, v107
	v_add3_u32 v154, v172, v82, v83
	v_add_u32_e32 v172, s6, v106
	v_add3_u32 v155, v172, v82, v83
	ds_read_b64 v[176:177], v154 offset:8192
	ds_read_b64 v[178:179], v155 offset:8192
	ds_read_b64 v[180:181], v154 offset:10240
	ds_read_b64 v[182:183], v155 offset:10240
	ds_read_b64 v[236:237], v154 offset:12288
	ds_read_b64 v[238:239], v155 offset:12288
	ds_read_b64 v[244:245], v154 offset:14336
	ds_read_b64 v[246:247], v155 offset:14336
	v_mfma_f32_16x16x32_bf16 v[46:49], v[46:49], v[156:159], 0
	v_mfma_f32_16x16x32_bf16 v[6:9], v[6:9], v[156:159], 0
	v_mfma_f32_16x16x32_bf16 v[42:45], v[42:45], v[160:163], v[46:49]
	v_mfma_f32_16x16x32_bf16 v[2:5], v[2:5], v[160:163], v[6:9]
	v_add_f32_e32 v54, v59, v60
	s_and_b64 vcc, s[0:1], s[40:41]
	v_cndmask_b32_e32 v60, v196, v54, vcc
	v_add_f32_e32 v54, v58, v61
	s_and_b64 vcc, s[0:1], s[42:43]
	v_cndmask_b32_e32 v61, v196, v54, vcc
	v_add_f32_e32 v54, v69, v62
	s_and_b64 vcc, s[0:1], s[44:45]
	v_cndmask_b32_e32 v66, v196, v54, vcc
	v_add_f32_e32 v54, v68, v63
	s_and_b64 vcc, s[0:1], s[46:47]
	v_cndmask_b32_e32 v67, v196, v54, vcc
	v_add_f32_e32 v50, v64, v50
	s_and_b64 vcc, s[0:1], s[48:49]
	v_cndmask_b32_e32 v68, v196, v50, vcc
	v_add_f32_e32 v50, v65, v51
	s_and_b64 vcc, s[0:1], s[50:51]
	v_cndmask_b32_e32 v69, v196, v50, vcc
	v_add_f32_e32 v50, v70, v52
	s_and_b64 vcc, s[0:1], s[52:53]
	v_cndmask_b32_e32 v76, v196, v50, vcc
	v_add_f32_e32 v50, v71, v53
	s_and_b64 vcc, s[0:1], s[54:55]
	v_cndmask_b32_e32 v77, v196, v50, vcc
	s_cmp_ge_u32 s10, s56
	s_cselect_b64 s[0:1], -1, 0
	s_cmp_lt_u32 s10, s57
	s_cselect_b64 s[8:9], -1, 0
	s_and_b64 s[0:1], s[0:1], s[8:9]
	s_and_b64 vcc, s[0:1], s[40:41]
	s_waitcnt lgkmcnt(8)
	v_add_f32_e32 v6, v164, v42
	v_cndmask_b32_e32 v130, v196, v6, vcc
	v_add_f32_e32 v6, v165, v43
	s_and_b64 vcc, s[0:1], s[42:43]
	v_cndmask_b32_e32 v131, v196, v6, vcc
	v_add_f32_e32 v6, v166, v44
	s_and_b64 vcc, s[0:1], s[44:45]
	v_cndmask_b32_e32 v132, v196, v6, vcc
	v_add_f32_e32 v6, v167, v45
	s_and_b64 vcc, s[0:1], s[46:47]
	v_cndmask_b32_e32 v133, v196, v6, vcc
	v_add_f32_e32 v2, v168, v2
	s_and_b64 vcc, s[0:1], s[48:49]
	v_cndmask_b32_e32 v136, v196, v2, vcc
	v_add_f32_e32 v2, v169, v3
	s_and_b64 vcc, s[0:1], s[50:51]
	v_cndmask_b32_e32 v137, v196, v2, vcc
	v_add_f32_e32 v0, v170, v4
	s_and_b64 vcc, s[0:1], s[52:53]
	v_cndmask_b32_e32 v138, v196, v0, vcc
	v_add_f32_e32 v0, v171, v5
	s_and_b64 vcc, s[0:1], s[54:55]
	v_max_f32_e32 v3, v76, v77
	v_cndmask_b32_e32 v139, v196, v0, vcc
	v_max_f32_e32 v0, v60, v61
	v_max_f32_e32 v2, v66, v67
	v_max3_f32 v3, v68, v69, v3
	v_max3_f32 v143, v0, v2, v3
	v_add_f32_e32 v0, 0x41000000, v75
	v_max_f32_e32 v3, v138, v139
	v_cmp_gt_f32_e32 vcc, v143, v0
	v_max_f32_e32 v0, v130, v131
	v_max_f32_e32 v2, v132, v133
	v_max3_f32 v3, v136, v137, v3
	v_max3_f32 v142, v0, v2, v3
	v_add_f32_e32 v0, 0x41000000, v74
	v_cmp_gt_f32_e64 s[0:1], v142, v0
	s_or_b64 vcc, vcc, s[0:1]
	v_mov_b32_e32 v140, v74
	v_mov_b32_e32 v141, v75
	v_mov_b64_e32 v[58:59], v[78:79]
	v_mov_b32_e32 v129, v74
	v_mov_b32_e32 v0, v75
	s_cbranch_vccz .LBB0_204
	ds_bpermute_b32 v0, v186, v143
	v_max_f32_e32 v2, v143, v143
	ds_bpermute_b32 v3, v186, v142
	v_max_f32_e32 v4, v142, v142
	s_waitcnt lgkmcnt(0)
	v_max_f32_e32 v0, v0, v0
	v_max_f32_e32 v0, v2, v0
	ds_bpermute_b32 v2, v187, v0
	s_waitcnt lgkmcnt(0)
	v_max3_f32 v141, v75, v0, v2
	v_max_f32_e32 v2, v3, v3
	v_max_f32_e32 v6, v4, v2
	ds_bpermute_b32 v7, v187, v6
	v_sub_f32_e32 v0, v75, v141
	v_exp_f32_e32 v0, v0
	s_waitcnt lgkmcnt(0)
	v_max3_f32 v140, v74, v6, v7
	v_sub_f32_e32 v6, v74, v140
	v_exp_f32_e32 v62, v6
	v_mov_b32_e32 v63, v0
	v_pk_mul_f32 v[40:41], v[40:41], v[0:1] op_sel_hi:[1,0]
	v_pk_mul_f32 v[38:39], v[38:39], v[0:1] op_sel_hi:[1,0]
	v_pk_mul_f32 v[36:37], v[36:37], v[0:1] op_sel_hi:[1,0]
	v_pk_mul_f32 v[34:35], v[34:35], v[0:1] op_sel_hi:[1,0]
	v_pk_mul_f32 v[24:25], v[24:25], v[0:1] op_sel_hi:[1,0]
	v_pk_mul_f32 v[22:23], v[22:23], v[0:1] op_sel_hi:[1,0]
	v_pk_mul_f32 v[16:17], v[16:17], v[0:1] op_sel_hi:[1,0]
	v_pk_mul_f32 v[14:15], v[14:15], v[0:1] op_sel_hi:[1,0]
	v_pk_mul_f32 v[58:59], v[78:79], v[62:63]
	v_pk_mul_f32 v[32:33], v[32:33], v[62:63] op_sel_hi:[1,0]
	v_pk_mul_f32 v[30:31], v[30:31], v[62:63] op_sel_hi:[1,0]
	v_pk_mul_f32 v[28:29], v[28:29], v[62:63] op_sel_hi:[1,0]
	v_pk_mul_f32 v[26:27], v[26:27], v[62:63] op_sel_hi:[1,0]
	v_pk_mul_f32 v[20:21], v[20:21], v[62:63] op_sel_hi:[1,0]
	v_pk_mul_f32 v[18:19], v[18:19], v[62:63] op_sel_hi:[1,0]
	v_pk_mul_f32 v[12:13], v[12:13], v[62:63] op_sel_hi:[1,0]
	v_pk_mul_f32 v[10:11], v[10:11], v[62:63] op_sel_hi:[1,0]
	v_mov_b32_e32 v129, v140
	v_mov_b32_e32 v0, v141
.LBB0_204:
	v_sub_f32_e32 v60, v60, v141
	v_exp_f32_e32 v147, v60
	v_sub_f32_e32 v60, v61, v141
	v_exp_f32_e32 v61, v60
	v_sub_f32_e32 v60, v66, v141
	v_exp_f32_e32 v149, v60
	v_sub_f32_e32 v60, v67, v141
	v_exp_f32_e32 v67, v60
	v_sub_f32_e32 v60, v68, v141
	v_exp_f32_e32 v151, v60
	v_sub_f32_e32 v60, v69, v141
	v_exp_f32_e32 v69, v60
	v_sub_f32_e32 v60, v76, v141
	v_exp_f32_e32 v153, v60
	v_sub_f32_e32 v60, v77, v141
	v_exp_f32_e32 v141, v60
	v_sub_f32_e32 v60, v130, v140
	v_exp_f32_e32 v146, v60
	v_sub_f32_e32 v60, v131, v140
	v_exp_f32_e32 v60, v60
	v_sub_f32_e32 v66, v132, v140
	v_exp_f32_e32 v148, v66
	v_sub_f32_e32 v66, v133, v140
	v_sub_f32_e32 v76, v138, v140
	v_exp_f32_e32 v66, v66
	v_sub_f32_e32 v68, v136, v140
	v_exp_f32_e32 v152, v76
	v_sub_f32_e32 v76, v139, v140
	v_exp_f32_e32 v150, v68
	v_sub_f32_e32 v68, v137, v140
	v_exp_f32_e32 v140, v76
	v_pk_add_f32 v[76:77], v[146:147], 0 op_sel_hi:[1,0]
	v_exp_f32_e32 v68, v68
	v_pk_add_f32 v[76:77], v[60:61], v[76:77]
	v_pk_add_f32 v[76:77], v[148:149], v[76:77]
	v_pk_add_f32 v[76:77], v[66:67], v[76:77]
	v_pk_add_f32 v[76:77], v[150:151], v[76:77]
	v_cvt_pk_bf16_f32 v143, v149, v67
	v_cvt_pk_bf16_f32 v144, v151, v69
	v_pk_add_f32 v[76:77], v[68:69], v[76:77]
	v_cvt_pk_bf16_f32 v131, v148, v66
	v_cvt_pk_bf16_f32 v132, v150, v68
	v_cvt_pk_bf16_f32 v142, v147, v61
	v_cvt_pk_bf16_f32 v145, v153, v141
	v_cvt_pk_bf16_f32 v130, v146, v60
	v_cvt_pk_bf16_f32 v133, v152, v140
	s_waitcnt lgkmcnt(0)
	v_mfma_f32_16x16x32_bf16 v[34:37], v[180:183], v[142:145], v[34:37]
	v_add_f32_e64 v76, v152, v76
	v_add_f32_e64 v77, v153, v77
	v_pk_add_f32 v[76:77], v[140:141], v[76:77]
	v_mfma_f32_16x16x32_bf16 v[26:29], v[180:183], v[130:133], v[26:29]
	v_pk_add_f32 v[76:77], v[58:59], v[76:77]
	v_mfma_f32_16x16x32_bf16 v[38:41], v[176:179], v[142:145], v[38:41]
	v_mfma_f32_16x16x32_bf16 v[30:33], v[176:179], v[130:133], v[30:33]
	v_mfma_f32_16x16x32_bf16 v[22:25], v[236:239], v[142:145], v[22:25]
	v_mfma_f32_16x16x32_bf16 v[18:21], v[236:239], v[130:133], v[18:21]
	v_mfma_f32_16x16x32_bf16 v[14:17], v[244:247], v[142:145], v[14:17]
	v_mfma_f32_16x16x32_bf16 v[10:13], v[244:247], v[130:133], v[10:13]
	s_branch .Lna_local_tail

.LBB0_211:
	s_xor_b32 s0, s6, 0x4000
	v_add_u32_e32 v0, s8, v122
	v_add_u32_e32 v4, s0, v94
	v_lshl_or_b32 v0, v0, 10, v126
	v_readfirstlane_b32 s0, v4
	v_lshl_add_u64 v[2:3], v[0:1], 1, s[28:29]
	s_mov_b32 m0, s0
	v_add_u32_e32 v0, s8, v125
	global_load_lds_dwordx4 v[2:3], off
	v_lshl_add_u64 v[2:3], v[0:1], 1, s[58:59]
	v_add_u32_e32 v0, s8, v123
	s_add_u32 m0, s0, 0x2000
	v_lshl_or_b32 v0, v0, 10, v127
	global_load_lds_dwordx4 v[2:3], off
	v_lshl_add_u64 v[2:3], v[0:1], 1, s[28:29]
	s_add_u32 m0, s0, 0x400
	v_add_u32_e32 v0, s8, v124
	global_load_lds_dwordx4 v[2:3], off
	v_lshl_add_u64 v[2:3], v[0:1], 1, s[58:59]
	s_add_u32 m0, s0, 0x2400
	s_nop 0
	global_load_lds_dwordx4 v[2:3], off

.Lna_local_tail:
	s_addk_i32 s83, 0x4000
	s_addk_i32 s97, 0x7c
	s_addk_i32 s98, 0x7c
	s_addk_i32 s99, 0x7c
	s_addk_i32 s30, 0x7c
	s_addk_i32 s4, 0x7c
	v_add_u32_e32 v128, 0x7c, v128
	s_waitcnt vmcnt(0)
	s_barrier
	s_mov_b32 s8, s5
	v_mov_b64_e32 v[78:79], v[76:77]
	v_mov_b32_e32 v74, v129
	v_mov_b32_e32 v75, v0
	s_branch .LBB0_195
